# attention K/V tile LDS-DMA loads: 16 per-lane 64-bit VALU address updates per 128 keys replaced by scalar running base pointers + constant 32-bit lane offsets (saddr form), all three attention loops
# baseline (speedup 1.0000x reference)
; #define LAS __attribute__((address_space(3)))
; __device__ __forceinline__ int v_rd_base(int lane) { return ((lane & 3) << 3) | (((lane >> 2) & 3) << 6) | (((lane >> 4) & 1) << 5) | (((lane >> 5) & 1) << 8); }
; #define AWAIT(more) do { if (more) asm volatile("s_waitcnt vmcnt(4)" ::: "memory"); else asm volatile("s_waitcnt vmcnt(0)" ::: "memory"); } while (0)
; #define ABAR() do { asm volatile("s_waitcnt lgkmcnt(0)" ::: "memory"); __builtin_amdgcn_s_barrier(); asm volatile("" ::: "memory"); } while (0)
; template <int QH> __device__ __forceinline__ void attn_dense_body(const bf16_t* __restrict__ Qb, const bf16_t* __restrict__ Kh, const bf16_t* __restrict__ Vh,
;                                                 bf16_t* __restrict__ Ob, int seq, float scale, char* lds, const int tid) {
;     ...
;   const int wid = __builtin_amdgcn_readfirstlane(tid >> 6), lane = tid & 63, r32 = lane & 31, hi = lane >> 5;
;   LAS unsigned char* L3 = (LAS unsigned char*)lds;
;   float* ws = (float*)(lds + 4 * SLOT) + wid * 64; float* li_l = ws; float* al_l = ws + 32;
;   float m_reg = -1e30f, l_reg = 0; f32x16 o[4] = {}; bf16x8 qr[8];
;   const bf16_t* Qw = Qb + (long)(wid * QBLK + r32) * LDQ + hi * 8;
; #pragma unroll
;   for (int d0 = 0; d0 < 8; ++d0) qr[d0] = *reinterpret_cast<const bf16x8*>(Qw + d0 * 16);
;   unsigned ko[2], vo[2];
; #pragma unroll
;   for (int n = 0; n < 2; ++n) { const int d = (n * 8 + wid) * 1024 + lane * 16;
;     { const int r = d >> 8, pos = (d & 255) >> 4, c = pos ^ (r & 7); ko[n] = (unsigned)(r * LDK + c * 8) * 2u; }
;     { const int sb = d >> 9, e = d & 511, kk = (sb >> 2) * 8 + (e >> 6), k = (kk & ~0xC) | ((kk & 4) << 1) | ((kk & 8) >> 1), c = (sb & 3) * 32 + ((e & 63) >> 1); vo[n] = (unsigned)(k * LDK + c) * 2u; } }
;   const int vrb = (int)(uintptr_t)lds + 16384 + v_rd_base(lane);
;     ...
;   f32x16 pA0, pA1, pB0, pB1; float mnA, mnB, alA, alB; bf16x8 pa0, pa1, pa2, pa3; const int NT = seq / KVBLK;
;   ADMA(0); ADMA(1);
;   asm volatile("s_waitcnt vmcnt(4)" ::: "memory"); ABAR();
;   if (2 < NT) ADMA(2);
;   qkt<QH>(pA0, pA1, KSLOT(0), qr, r32, hi); partialSM(pA0, pA1, m_reg, mnA, alA, C, thr);
;   AWAIT(2 < NT); ABAR();
.LBB0_96:
	s_mul_i32 s8, s10, 0x1100
	s_lshl_b32 s12, s12, 8
	s_mul_hi_i32 s9, s10, 0x1100
	s_add_u32 s8, s8, s12
	s_addc_u32 s9, s9, 0
	s_lshl_b64 s[12:13], s[8:9], 11
	s_lshl_b32 s66, s11, 7
	s_or_b32 s16, s12, s66
	s_mul_i32 s9, s10, 0x440000
	s_lshl_b32 s15, s14, 7
	s_mul_hi_i32 s8, s10, 0x440000
	s_add_u32 s18, s9, s15
	s_mov_b32 s17, s13
	s_addc_u32 s19, s8, 0
	s_mov_b64 s[8:9], -1
	s_andn2_b64 vcc, exec, s[54:55]
	v_lshlrev_b32_e32 v144, 1, v130
	s_mul_hi_i32 s71, s10, 0x880000
	s_mul_i32 s72, s10, 0x880000
	s_cbranch_vccnz .LBB0_127
	s_lshl_b64 s[8:9], s[16:17], 1
	s_add_u32 s22, s28, s8
	s_addc_u32 s23, s29, s9
	s_lshl_b64 s[8:9], s[18:19], 1
	s_add_u32 s20, s30, s8
	s_addc_u32 s21, s31, s9
	s_add_u32 s8, s56, s8
	v_readfirstlane_b32 s10, v146
	s_addc_u32 s9, s57, s9
	s_ashr_i32 s15, s10, 6
	s_and_b32 s10, s10, 0x3fffffc0
	s_lshl_b32 s10, s10, 2
	s_add_i32 s10, s10, 0
	s_add_i32 s67, s10, 0x20000
	s_lshl_b32 s10, s15, 5
	v_or_b32_e32 v0, s10, v128
	v_ashrrev_i32_e32 v1, 31, v0
	v_lshlrev_b64 v[0:1], 12, v[0:1]
	v_lshl_add_u64 v[0:1], s[22:23], 0, v[0:1]
	v_lshl_add_u64 v[0:1], v[0:1], 0, v[144:145]
	flat_load_dwordx4 v[124:127], v[0:1]
	flat_load_dwordx4 v[120:123], v[0:1] offset:32
	flat_load_dwordx4 v[116:119], v[0:1] offset:64
	flat_load_dwordx4 v[112:115], v[0:1] offset:96
	flat_load_dwordx4 v[108:111], v[0:1] offset:128
	flat_load_dwordx4 v[104:107], v[0:1] offset:160
	flat_load_dwordx4 v[100:103], v[0:1] offset:192
	flat_load_dwordx4 v[96:99], v[0:1] offset:224
	s_lshl_b32 s22, s15, 10
	s_ashr_i32 s15, s22, 8
	v_or_b32_e32 v0, s22, v129
	s_and_b32 s23, s15, 0x1ffff0
	s_lshr_b32 s15, s15, 1
	v_ashrrev_i32_e32 v1, 8, v0
	s_and_b32 s15, s15, 4
	v_bitop3_b32 v2, v1, v131, 7 bitop3:0x6c
	v_lshlrev_b32_e32 v1, 11, v1
	s_or_b32 s23, s23, s15
	v_lshl_or_b32 v48, v2, 4, v1
	v_or_b32_e32 v1, s23, v147
	v_lshrrev_b32_e32 v0, 3, v0
	s_add_i32 s15, s22, 0x2000
	v_and_b32_e32 v56, 0xc0, v0
	v_lshlrev_b32_e32 v0, 11, v1
	v_or_b32_e32 v1, s15, v129
	s_ashr_i32 s15, s15, 8
	s_and_b32 s24, s15, 0x1ffff0
	s_lshr_b32 s15, s15, 1
	s_and_b32 s15, s15, 4
	s_add_i32 s26, s22, 0
	v_ashrrev_i32_e32 v2, 8, v1
	s_or_b32 s24, s24, s15
	s_add_i32 s15, s26, 0x4000
	s_mov_b32 m0, s26
	v_or3_b32 v0, v0, v56, v172
	v_bitop3_b32 v3, v2, v131, 7 bitop3:0x6c
	v_lshlrev_b32_e32 v2, 11, v2
	global_load_lds_dwordx4 v48, s[20:21]
	s_mov_b32 m0, s15
	v_lshl_or_b32 v50, v3, 4, v2
	v_or_b32_e32 v2, s24, v147
	v_lshrrev_b32_e32 v1, 3, v1
	global_load_lds_dwordx4 v0, s[8:9]
	s_add_i32 m0, s26, 0x2000
	v_and_b32_e32 v1, 0xc0, v1
	v_lshlrev_b32_e32 v2, 11, v2
	global_load_lds_dwordx4 v50, s[20:21]
	s_add_i32 m0, s26, 0x6000
	v_or3_b32 v1, v2, v1, v172
	s_add_u32 s38, s20, 0x20000
	global_load_lds_dwordx4 v1, s[8:9]
	s_addc_u32 s39, s21, 0
	s_add_i32 m0, s26, 0x8000
	s_add_u32 s40, s8, 0x20000
	s_addc_u32 s41, s9, 0
	s_add_i32 s15, s26, 0xc000
	global_load_lds_dwordx4 v48, s[38:39]
	s_mov_b32 m0, s15
	v_add_u32_e32 v4, 0, v175
	global_load_lds_dwordx4 v0, s[40:41]
	s_add_i32 m0, s26, 0xa000
	v_add_u32_e32 v8, 0, v182
	global_load_lds_dwordx4 v50, s[38:39]
	s_add_i32 m0, s26, 0xe000
	s_add_u32 s20, s20, 0x40000
	global_load_lds_dwordx4 v1, s[40:41]
	s_addc_u32 s21, s21, 0
	s_add_i32 m0, s26, 0x10000
	s_waitcnt vmcnt(4)
	s_add_u32 s8, s8, 0x40000
	s_waitcnt lgkmcnt(0)
	s_barrier
	s_addc_u32 s9, s9, 0
	s_add_i32 s15, s26, 0x14000
	global_load_lds_dwordx4 v48, s[20:21]
	s_mov_b32 m0, s15
	s_mov_b32 s36, s37
	global_load_lds_dwordx4 v0, s[8:9]
	s_add_i32 m0, s26, 0x12000
	s_mov_b32 s38, s37
	global_load_lds_dwordx4 v50, s[20:21]
	s_add_i32 m0, s26, 0x16000
	s_mov_b32 s39, s37
	global_load_lds_dwordx4 v1, s[8:9]
	ds_read_b128 v[0:3], v4
	ds_read_b128 v[4:7], v4 offset:8192
	s_waitcnt vmcnt(0) lgkmcnt(0)
	v_mfma_f32_32x32x16_bf16 v[32:47], v[4:7], v[124:127], 0
	v_add_u32_e32 v4, 0, v176
	s_mov_b32 s40, s37
	s_mov_b32 s41, s37
	s_mov_b32 s42, s37
	s_mov_b32 s43, s37
	s_mov_b32 s44, s37
	s_mov_b32 s45, s37
	v_mfma_f32_32x32x16_bf16 v[16:31], v[0:3], v[124:127], 0
	ds_read_b128 v[0:3], v4
	ds_read_b128 v[4:7], v4 offset:8192
	s_mov_b32 s46, s37
	s_mov_b32 s47, s37
	s_mov_b32 s48, s37
	s_mov_b32 s49, s37
	s_mov_b32 s50, s37
	s_mov_b32 s51, s37
	s_waitcnt lgkmcnt(0)
	v_mfma_f32_32x32x16_bf16 v[32:47], v[4:7], v[120:123], v[32:47]
	v_add_u32_e32 v4, 0, v177
	s_mov_b32 s15, s37
	v_mov_b32_e32 v49, v145
	v_mov_b32_e32 v51, v145
	s_mov_b32 s27, 4
	s_mov_b32 s73, 0x10000
	v_lshl_add_u32 v184, v128, 2, s67
	v_mfma_f32_32x32x16_bf16 v[16:31], v[0:3], v[120:123], v[16:31]
	ds_read_b128 v[0:3], v4
	ds_read_b128 v[4:7], v4 offset:8192
	v_mov_b32_e32 v185, 0
	s_waitcnt lgkmcnt(0)
	v_mfma_f32_32x32x16_bf16 v[32:47], v[4:7], v[116:119], v[32:47]
	v_add_u32_e32 v4, 0, v178
	v_mfma_f32_32x32x16_bf16 v[16:31], v[0:3], v[116:119], v[16:31]
	ds_read_b128 v[0:3], v4
	ds_read_b128 v[4:7], v4 offset:8192
	s_waitcnt lgkmcnt(0)
	v_mfma_f32_32x32x16_bf16 v[32:47], v[4:7], v[112:115], v[32:47]
	v_add_u32_e32 v4, 0, v179
	v_mfma_f32_32x32x16_bf16 v[16:31], v[0:3], v[112:115], v[16:31]
	ds_read_b128 v[0:3], v4
	ds_read_b128 v[4:7], v4 offset:8192
	s_waitcnt lgkmcnt(0)
	v_mfma_f32_32x32x16_bf16 v[32:47], v[4:7], v[108:111], v[32:47]
	v_add_u32_e32 v4, 0, v180
	v_mfma_f32_32x32x16_bf16 v[16:31], v[0:3], v[108:111], v[16:31]
	ds_read_b128 v[0:3], v4
	ds_read_b128 v[4:7], v4 offset:8192
	ds_read_b128 v[52:55], v8 offset:8192
	s_waitcnt lgkmcnt(1)
	v_mfma_f32_32x32x16_bf16 v[32:47], v[4:7], v[104:107], v[32:47]
	v_add_u32_e32 v4, 0, v181
	v_mfma_f32_32x32x16_bf16 v[16:31], v[0:3], v[104:107], v[16:31]
	ds_read_b128 v[0:3], v4
	ds_read_b128 v[4:7], v4 offset:8192
	s_waitcnt lgkmcnt(1)
	v_mfma_f32_32x32x16_bf16 v[16:31], v[0:3], v[100:103], v[16:31]
	ds_read_b128 v[0:3], v8
	s_waitcnt vmcnt(4)
	s_waitcnt lgkmcnt(0)
	s_barrier
; #define AWAIT(more) do { if (more) asm volatile("s_waitcnt vmcnt(4)" ::: "memory"); else asm volatile("s_waitcnt vmcnt(0)" ::: "memory"); } while (0)
; #define ABAR() do { asm volatile("s_waitcnt lgkmcnt(0)" ::: "memory"); __builtin_amdgcn_s_barrier(); asm volatile("" ::: "memory"); } while (0)
; __device__ __forceinline__ void partialSM(f32x16& p0, f32x16& p1, float& m_reg, float& mn, float& alpha, float C, float thr) {
;   float pmax = p0[0]; for (int r = 1; r < 16; ++r) pmax = fmaxf(pmax, p0[r]); for (int r = 0; r < 16; ++r) pmax = fmaxf(pmax, p1[r]);
;   { auto rr = __builtin_amdgcn_permlane32_swap(__float_as_uint(pmax), __float_as_uint(pmax), false, false);
;     pmax = fmaxf(__uint_as_float(rr[0]), __uint_as_float(rr[1])); }
;   if (__builtin_expect(__all(pmax - m_reg <= thr), 1)) { mn = m_reg; alpha = 1.f; }
;   else { mn = fmaxf(m_reg, pmax); alpha = __builtin_amdgcn_exp2f((m_reg - mn) * C); m_reg = mn; }
;   float mnC = -mn * C;
;   for (int r = 0; r < 16; ++r) p0[r] = fmaf(p0[r], C, mnC); for (int r = 0; r < 16; ++r) p1[r] = fmaf(p1[r], C, mnC);
;   for (int r = 0; r < 16; ++r) p0[r] = __builtin_amdgcn_exp2f(p0[r]);
; }
; template <int QH> __device__ __forceinline__ void attn_dense_body(const bf16_t* __restrict__ Qb, const bf16_t* __restrict__ Kh, const bf16_t* __restrict__ Vh,
;                                                 bf16_t* __restrict__ Ob, int seq, float scale, char* lds, const int tid) {
;     ...
;   qkt<QH>(pA0, pA1, KSLOT(0), qr, r32, hi); partialSM(pA0, pA1, m_reg, mnA, alA, C, thr);
;   AWAIT(2 < NT); ABAR();
;   for (int j = 1; j + 1 < NT; j += 2) {
;     if (j + 2 < NT) ADMA(j + 2);
	s_waitcnt lgkmcnt(1)
	v_mfma_f32_32x32x16_bf16 v[32:47], v[4:7], v[100:103], v[32:47]
	s_waitcnt lgkmcnt(0)
	v_mfma_f32_32x32x16_bf16 v[16:31], v[0:3], v[96:99], v[16:31]
	v_mov_b64_e32 v[0:1], s[36:37]
	v_mov_b64_e32 v[2:3], s[38:39]
	v_mov_b64_e32 v[4:5], s[40:41]
	v_mov_b64_e32 v[6:7], s[42:43]
	v_mov_b64_e32 v[8:9], s[44:45]
	v_mov_b64_e32 v[10:11], s[46:47]
	v_mov_b64_e32 v[12:13], s[48:49]
	v_mfma_f32_32x32x16_bf16 v[32:47], v[52:55], v[96:99], v[32:47]
	s_nop 3
	v_max_f32_e32 v52, v17, v17
	v_max_f32_e32 v53, v16, v16
	v_max_f32_e32 v52, v53, v52
	v_max3_f32 v52, v52, v18, v19
	v_max3_f32 v52, v52, v20, v21
	v_max3_f32 v52, v52, v22, v23
	v_max3_f32 v52, v52, v24, v25
	v_max3_f32 v52, v52, v26, v27
	v_max3_f32 v52, v52, v28, v29
	v_max3_f32 v52, v52, v30, v31
	v_max3_f32 v52, v52, v32, v33
	v_max3_f32 v52, v52, v34, v35
	v_max3_f32 v52, v52, v36, v37
	v_max3_f32 v52, v52, v38, v39
	v_max3_f32 v52, v52, v40, v41
	v_max3_f32 v52, v52, v42, v43
	v_max3_f32 v52, v52, v44, v45
	v_max3_f32 v52, v52, v46, v47
	v_mov_b32_e32 v53, v52
	s_nop 1
	v_permlane32_swap_b32_e32 v52, v53
	v_max_f32_e32 v53, v53, v53
	v_max_f32_e32 v52, v52, v52
	v_max_f32_e32 v52, v52, v53
	v_mov_b64_e32 v[14:15], s[50:51]
	v_add_f32_e32 v53, 0x7149f2ca, v52
	s_mov_b32 s40, 0x42b504f3
	v_cmp_ge_f32_e32 vcc, s40, v53
	s_cmp_eq_u64 vcc, exec
	v_max_f32_e32 v52, 0xf149f2ca, v52
	s_cselect_b64 vcc, -1, 0
	v_cndmask_b32_e32 v199, v52, v197, vcc
	v_sub_f32_e32 v53, 0xf149f2ca, v52
	v_mul_f32_e32 v52, 0xbe0293ee, v199
	v_fmamk_f32 v16, v16, 0x3e0293ee, v52
	v_exp_f32_e32 v209, v16
	v_fmamk_f32 v16, v17, 0x3e0293ee, v52
	v_exp_f32_e32 v210, v16
	v_fmamk_f32 v16, v18, 0x3e0293ee, v52
	v_exp_f32_e32 v211, v16
	v_fmamk_f32 v16, v19, 0x3e0293ee, v52
	v_exp_f32_e32 v213, v16
	v_fmamk_f32 v16, v20, 0x3e0293ee, v52
	v_exp_f32_e32 v215, v16
	v_fmamk_f32 v16, v21, 0x3e0293ee, v52
	v_exp_f32_e32 v216, v16
	v_fmamk_f32 v16, v22, 0x3e0293ee, v52
	v_exp_f32_e32 v212, v16
	v_fmamk_f32 v16, v23, 0x3e0293ee, v52
	v_exp_f32_e32 v214, v16
	v_fmamk_f32 v16, v24, 0x3e0293ee, v52
	v_exp_f32_e32 v201, v16
	v_fmamk_f32 v16, v25, 0x3e0293ee, v52
	v_exp_f32_e32 v203, v16
	v_fmamk_f32 v16, v26, 0x3e0293ee, v52
	v_exp_f32_e32 v205, v16
	v_fmamk_f32 v16, v27, 0x3e0293ee, v52
	v_exp_f32_e32 v207, v16
	v_fmamk_f32 v16, v28, 0x3e0293ee, v52
	v_mul_f32_e32 v53, 0x3e0293ee, v53
	v_exp_f32_e32 v202, v16
	v_fmamk_f32 v16, v29, 0x3e0293ee, v52
	v_add_u32_e32 v17, s22, v183
	v_exp_f32_e32 v53, v53
	v_exp_f32_e32 v204, v16
	v_fmamk_f32 v16, v30, 0x3e0293ee, v52
	s_lshl_b64 s[20:21], s[14:15], 8
	v_lshrrev_b32_e32 v17, 3, v17
	v_exp_f32_e32 v206, v16
	v_add_lshl_u32 v16, s24, v147, 11
	v_and_b32_e32 v17, 0xc0, v17
	s_add_u32 s8, s61, s72
	v_or3_b32 v16, v172, v16, v17
	v_mov_b32_e32 v17, v145
	s_addc_u32 s9, s62, s71
	v_mov_b32_e32 v134, v16
	v_mov_b32_e32 v135, s8
	v_add_lshl_u32 v16, s23, v147, 11
	v_pk_fma_f32 v[156:157], v[46:47], s[52:53], v[52:53] op_sel_hi:[1,0,0]
	v_pk_fma_f32 v[158:159], v[44:45], s[52:53], v[52:53] op_sel_hi:[1,0,0]
	v_pk_fma_f32 v[160:161], v[42:43], s[52:53], v[52:53] op_sel_hi:[1,0,0]
	v_pk_fma_f32 v[162:163], v[40:41], s[52:53], v[52:53] op_sel_hi:[1,0,0]
	v_pk_fma_f32 v[164:165], v[38:39], s[52:53], v[52:53] op_sel_hi:[1,0,0]
	v_pk_fma_f32 v[166:167], v[36:37], s[52:53], v[52:53] op_sel_hi:[1,0,0]
	v_pk_fma_f32 v[168:169], v[34:35], s[52:53], v[52:53] op_sel_hi:[1,0,0]
	v_pk_fma_f32 v[170:171], v[32:33], s[52:53], v[52:53] op_sel_hi:[1,0,0]
	v_fmac_f32_e32 v52, 0x3e0293ee, v31
	v_or3_b32 v16, v172, v16, v56
	v_exp_f32_e32 v208, v52
	v_mov_b32_e32 v136, v16
	v_mov_b32_e32 v137, s9
	s_add_u32 s8, s63, s72
	s_addc_u32 s9, s64, s71
	v_cndmask_b32_e64 v200, v53, 1.0, vcc
	v_mov_b32_e32 v138, v50
	v_mov_b32_e32 v139, s8
	v_mov_b32_e32 v140, v48
	v_mov_b32_e32 v141, s9
	v_mov_b64_e32 v[62:63], v[14:15]
	v_mov_b64_e32 v[46:47], v[14:15]
	v_mov_b64_e32 v[30:31], v[14:15]
	s_movk_i32 s44, 0x1000
	v_mov_b64_e32 v[60:61], v[12:13]
	v_mov_b64_e32 v[58:59], v[10:11]
	v_mov_b64_e32 v[56:57], v[8:9]
	v_mov_b64_e32 v[54:55], v[6:7]
	v_mov_b64_e32 v[52:53], v[4:5]
	v_mov_b64_e32 v[50:51], v[2:3]
	v_mov_b64_e32 v[48:49], v[0:1]
	v_mov_b64_e32 v[44:45], v[12:13]
	v_mov_b64_e32 v[42:43], v[10:11]
	v_mov_b64_e32 v[40:41], v[8:9]
	v_mov_b64_e32 v[38:39], v[6:7]
	v_mov_b64_e32 v[36:37], v[4:5]
	v_mov_b64_e32 v[34:35], v[2:3]
	v_mov_b64_e32 v[32:33], v[0:1]
	v_mov_b64_e32 v[28:29], v[12:13]
	v_mov_b64_e32 v[26:27], v[10:11]
	v_mov_b64_e32 v[24:25], v[8:9]
	v_mov_b64_e32 v[22:23], v[6:7]
	v_mov_b64_e32 v[20:21], v[4:5]
	v_mov_b64_e32 v[18:19], v[2:3]
	v_mov_b64_e32 v[16:17], v[0:1]
	v_readfirstlane_b32 s46, v135
	v_readfirstlane_b32 s47, v137
	v_readfirstlane_b32 s42, v139
	v_readfirstlane_b32 s43, v141
	s_add_u32 s46, s46, s20
	s_addc_u32 s47, s47, s21
	s_add_u32 s46, s46, 0x9dc9000
	s_addc_u32 s47, s47, 0
	s_add_u32 s42, s42, s20
	s_addc_u32 s43, s43, s21
	s_add_u32 s42, s42, 0x9dc9000
	s_addc_u32 s43, s43, 0
.LBB0_98:
	s_add_i32 s8, s27, -1
	s_cmp_ge_u32 s8, s70
	s_cselect_b64 s[22:23], -1, 0
	s_and_b64 vcc, exec, s[22:23]
	s_cbranch_vccnz .LBB0_100
	s_add_i32 s8, s73, 0x8000
	s_and_b32 s8, s8, 0x18000
	s_add_i32 s8, s26, s8
	s_add_i32 s9, s8, 0x4000
	s_mov_b32 m0, s8
	s_nop 0
	global_load_lds_dwordx4 v140, s[42:43]
	s_mov_b32 m0, s9
	s_nop 0
	global_load_lds_dwordx4 v136, s[46:47]
	s_add_i32 m0, s8, 0x2000
	s_nop 0
	global_load_lds_dwordx4 v138, s[42:43]
	s_add_i32 m0, s8, 0x6000
	s_nop 0
	global_load_lds_dwordx4 v134, s[46:47]

; #define SBAR() __builtin_amdgcn_sched_barrier(0)
; template <int QH> __device__ __forceinline__ void attn_dense_body(const bf16_t* __restrict__ Qb, const bf16_t* __restrict__ Kh, const bf16_t* __restrict__ Vh,
;                                                 bf16_t* __restrict__ Ob, int seq, float scale, char* lds, const int tid) {
;     ...
;     if (j + 3 < NT) ADMA(j + 3);
;     SBAR(); qkt<QH>(pA0, pA1, KSLOT(j + 1), qr, r32, hi);
.LBB0_108:
	s_cmp_ge_u32 s27, s70
	s_cselect_b64 s[22:23], -1, 0
	s_and_b64 vcc, exec, s[22:23]
	s_cbranch_vccnz .LBB0_110
	s_add_i32 s24, s26, s38
	s_add_i32 s25, s24, 0x4000
	s_add_u32 s42, s42, 0x20000
	s_addc_u32 s43, s43, 0
	s_add_u32 s46, s46, 0x20000
	s_addc_u32 s47, s47, 0
	s_mov_b32 m0, s24
	s_nop 0
	global_load_lds_dwordx4 v140, s[42:43]
	s_mov_b32 m0, s25
	s_nop 0
	global_load_lds_dwordx4 v136, s[46:47]
	s_add_i32 m0, s24, 0x2000
	s_nop 0
	global_load_lds_dwordx4 v138, s[42:43]
	s_add_i32 m0, s24, 0x6000
	s_nop 0
	global_load_lds_dwordx4 v134, s[46:47]
	s_sub_u32 s42, s42, 0x20000
	s_subb_u32 s43, s43, 0
	s_sub_u32 s46, s46, 0x20000
	s_subb_u32 s47, s47, 0

; #define AWAIT(more) do { if (more) asm volatile("s_waitcnt vmcnt(4)" ::: "memory"); else asm volatile("s_waitcnt vmcnt(0)" ::: "memory"); } while (0)
; #define ABAR() do { asm volatile("s_waitcnt lgkmcnt(0)" ::: "memory"); __builtin_amdgcn_s_barrier(); asm volatile("" ::: "memory"); } while (0)
; #define RESC(a) do { if (__any((a) < 1.f)) { if (hi == 0) al_l[r32] = (a); asm volatile("s_waitcnt lgkmcnt(0)" ::: "memory"); \
;     for (int d = 0; d < 4; ++d) for (int r = 0; r < 16; ++r) o[d][r] *= al_l[crow(r, hi)]; } } while (0)
; __device__ __forceinline__ void partialSM(f32x16& p0, f32x16& p1, float& m_reg, float& mn, float& alpha, float C, float thr) {
;     ...
;     pmax = fmaxf(__uint_as_float(rr[0]), __uint_as_float(rr[1])); }
;   if (__builtin_expect(__all(pmax - m_reg <= thr), 1)) { mn = m_reg; alpha = 1.f; }
;   else { mn = fmaxf(m_reg, pmax); alpha = __builtin_amdgcn_exp2f((m_reg - mn) * C); m_reg = mn; }
;   float mnC = -mn * C;
;   for (int r = 0; r < 16; ++r) p0[r] = fmaf(p0[r], C, mnC); for (int r = 0; r < 16; ++r) p1[r] = fmaf(p1[r], C, mnC);
;   for (int r = 0; r < 16; ++r) p0[r] = __builtin_amdgcn_exp2f(p0[r]);
; }
; __device__ __forceinline__ void finishSM(f32x16& p0, f32x16& p1, float alpha, float& l_reg, bf16x8& pa0, bf16x8& pa1, bf16x8& pa2, bf16x8& pa3) {
;   for (int r = 0; r < 16; ++r) p1[r] = __builtin_amdgcn_exp2f(p1[r]);
;   float ps = 0; for (int r = 0; r < 16; ++r) ps += p0[r]; for (int r = 0; r < 16; ++r) ps += p1[r];
;   { auto rr = __builtin_amdgcn_permlane32_swap(__float_as_uint(ps), __float_as_uint(ps), false, false);
;     ps = __uint_as_float(rr[0]) + __uint_as_float(rr[1]); }
;   l_reg = l_reg * alpha + ps;
; template <int QH> __device__ __forceinline__ void attn_dense_body(const bf16_t* __restrict__ Qb, const bf16_t* __restrict__ Kh, const bf16_t* __restrict__ Vh,
;                                                 bf16_t* __restrict__ Ob, int seq, float scale, char* lds, const int tid) {
;     ...
;     pv_d0(o, VSLOT(j), pa0, pa1, pa2, pa3); partialSM(pA0, pA1, m_reg, mnA, alA, C, thr);
;     AWAIT(j + 3 < NT); ABAR();
;     RESC(alA);
;   }
.LBB0_118:
	v_add_f32_e32 v153, v156, v157
	v_cndmask_b32_e64 v199, v152, v143, s[8:9]
	v_fmac_f32_e32 v153, v200, v185
	v_add_f32_e32 v185, v150, v151
	v_mul_f32_e32 v150, 0xbe0293ee, v199
	v_mov_b32_e32 v143, v150
	v_fmamk_f32 v80, v80, 0x3e0293ee, v150
	v_fmamk_f32 v81, v81, 0x3e0293ee, v150
	v_fmamk_f32 v82, v82, 0x3e0293ee, v150
	v_fmamk_f32 v83, v83, 0x3e0293ee, v150
	v_fmamk_f32 v84, v84, 0x3e0293ee, v150
	v_fmamk_f32 v85, v85, 0x3e0293ee, v150
	v_fmamk_f32 v86, v86, 0x3e0293ee, v150
	v_fmamk_f32 v87, v87, 0x3e0293ee, v150
	v_fmamk_f32 v88, v88, 0x3e0293ee, v150
	v_fmamk_f32 v89, v89, 0x3e0293ee, v150
	v_fmamk_f32 v90, v90, 0x3e0293ee, v150
	v_fmamk_f32 v91, v91, 0x3e0293ee, v150
	v_fmamk_f32 v92, v92, 0x3e0293ee, v150
	v_fmamk_f32 v93, v93, 0x3e0293ee, v150
	v_fmamk_f32 v94, v94, 0x3e0293ee, v150
	v_fmac_f32_e32 v143, 0x3e0293ee, v95
	v_exp_f32_e32 v209, v80
	v_exp_f32_e32 v210, v81
	v_exp_f32_e32 v211, v82
	v_exp_f32_e32 v213, v83
	v_exp_f32_e32 v215, v84
	v_exp_f32_e32 v216, v85
	v_exp_f32_e32 v212, v86
	v_exp_f32_e32 v214, v87
	v_exp_f32_e32 v201, v88
	v_exp_f32_e32 v203, v89
	v_exp_f32_e32 v205, v90
	v_exp_f32_e32 v207, v91
	v_exp_f32_e32 v202, v92
	v_exp_f32_e32 v204, v93
	v_exp_f32_e32 v206, v94
	v_exp_f32_e32 v208, v143
	v_fmac_f32_e32 v185, v153, v158
	v_pk_fma_f32 v[170:171], v[64:65], s[52:53], v[150:151] op_sel_hi:[1,0,0]
	v_pk_fma_f32 v[168:169], v[66:67], s[52:53], v[150:151] op_sel_hi:[1,0,0]
	v_pk_fma_f32 v[166:167], v[68:69], s[52:53], v[150:151] op_sel_hi:[1,0,0]
	v_pk_fma_f32 v[164:165], v[70:71], s[52:53], v[150:151] op_sel_hi:[1,0,0]
	v_pk_fma_f32 v[162:163], v[72:73], s[52:53], v[150:151] op_sel_hi:[1,0,0]
	v_pk_fma_f32 v[160:161], v[74:75], s[52:53], v[150:151] op_sel_hi:[1,0,0]
	v_pk_fma_f32 v[158:159], v[76:77], s[52:53], v[150:151] op_sel_hi:[1,0,0]
	v_pk_fma_f32 v[156:157], v[78:79], s[52:53], v[150:151] op_sel_hi:[1,0,0]
	s_add_u32 s42, s42, s74
	s_addc_u32 s43, s43, s75
	s_add_u32 s46, s46, s74
	s_addc_u32 s47, s47, s75
	s_add_i32 s27, s27, 2
	s_and_b64 vcc, exec, s[22:23]
	s_cbranch_vccnz .LBB0_120
	s_mov_b32 s73, s15
	v_mov_b32_e32 v200, v142
	s_branch .LBB0_98

; #define LAS __attribute__((address_space(3)))
; __device__ __forceinline__ int v_rd_base(int lane) { return ((lane & 3) << 3) | (((lane >> 2) & 3) << 6) | (((lane >> 4) & 1) << 5) | (((lane >> 5) & 1) << 8); }
; #define AWAIT(more) do { if (more) asm volatile("s_waitcnt vmcnt(4)" ::: "memory"); else asm volatile("s_waitcnt vmcnt(0)" ::: "memory"); } while (0)
; #define ABAR() do { asm volatile("s_waitcnt lgkmcnt(0)" ::: "memory"); __builtin_amdgcn_s_barrier(); asm volatile("" ::: "memory"); } while (0)
; template <int QH> __device__ __forceinline__ void attn_dense_body(const bf16_t* __restrict__ Qb, const bf16_t* __restrict__ Kh, const bf16_t* __restrict__ Vh,
;                                                 bf16_t* __restrict__ Ob, int seq, float scale, char* lds, const int tid) {
;     ...
;   const int wid = __builtin_amdgcn_readfirstlane(tid >> 6), lane = tid & 63, r32 = lane & 31, hi = lane >> 5;
;   LAS unsigned char* L3 = (LAS unsigned char*)lds;
;   float* ws = (float*)(lds + 4 * SLOT) + wid * 64; float* li_l = ws; float* al_l = ws + 32;
;   float m_reg = -1e30f, l_reg = 0; f32x16 o[4] = {}; bf16x8 qr[8];
;   const bf16_t* Qw = Qb + (long)(wid * QBLK + r32) * LDQ + hi * 8;
; #pragma unroll
;   for (int d0 = 0; d0 < 8; ++d0) qr[d0] = *reinterpret_cast<const bf16x8*>(Qw + d0 * 16);
;   unsigned ko[2], vo[2];
; #pragma unroll
;   for (int n = 0; n < 2; ++n) { const int d = (n * 8 + wid) * 1024 + lane * 16;
;     { const int r = d >> 8, pos = (d & 255) >> 4, c = pos ^ (r & 7); ko[n] = (unsigned)(r * LDK + c * 8) * 2u; }
;     { const int sb = d >> 9, e = d & 511, kk = (sb >> 2) * 8 + (e >> 6), k = (kk & ~0xC) | ((kk & 4) << 1) | ((kk & 8) >> 1), c = (sb & 3) * 32 + ((e & 63) >> 1); vo[n] = (unsigned)(k * LDK + c) * 2u; } }
;   const int vrb = (int)(uintptr_t)lds + 16384 + v_rd_base(lane);
;     ...
;   f32x16 pA0, pA1, pB0, pB1; float mnA, mnB, alA, alB; bf16x8 pa0, pa1, pa2, pa3; const int NT = seq / KVBLK;
;   ADMA(0); ADMA(1);
;   asm volatile("s_waitcnt vmcnt(4)" ::: "memory"); ABAR();
;   if (2 < NT) ADMA(2);
;   qkt<QH>(pA0, pA1, KSLOT(0), qr, r32, hi); partialSM(pA0, pA1, m_reg, mnA, alA, C, thr);
;   AWAIT(2 < NT); ABAR();
.LBB0_127:
	s_and_b64 vcc, exec, s[8:9]
	s_cbranch_vccz .LBB0_86
	s_and_b32 s10, s11, 1
	s_lshl_b64 s[8:9], s[16:17], 1
	s_add_u32 s20, s28, s8
	s_addc_u32 s21, s29, s9
	s_lshl_b64 s[8:9], s[18:19], 1
	s_add_u32 s18, s30, s8
	s_addc_u32 s19, s31, s9
	s_add_u32 s16, s56, s8
	s_addc_u32 s17, s57, s9
	s_cmp_eq_u32 s10, 0
	s_mov_b64 s[8:9], -1
	s_cbranch_scc1 .LBB0_159
	v_readfirstlane_b32 s8, v146
	s_ashr_i32 s9, s8, 6
	s_lshl_b32 s10, s9, 5
	v_or_b32_e32 v0, s10, v128
	v_ashrrev_i32_e32 v1, 31, v0
	v_lshlrev_b64 v[0:1], 12, v[0:1]
	v_lshl_add_u64 v[0:1], s[20:21], 0, v[0:1]
	v_lshl_add_u64 v[0:1], v[0:1], 0, v[144:145]
	flat_load_dwordx4 v[108:111], v[0:1] offset:128
	flat_load_dwordx4 v[104:107], v[0:1] offset:160
	flat_load_dwordx4 v[100:103], v[0:1] offset:192
	flat_load_dwordx4 v[96:99], v[0:1] offset:224
	s_and_b32 s8, s8, 0x3fffffc0
	s_lshl_b32 s8, s8, 2
	s_add_i32 s8, s8, 0
	s_add_i32 s67, s8, 0x20000
	s_lshl_b32 s8, s9, 10
	s_ashr_i32 s9, s8, 8
	v_or_b32_e32 v0, s8, v129
	s_and_b32 s15, s9, 0x1ffff0
	s_lshr_b32 s9, s9, 1
	v_ashrrev_i32_e32 v1, 8, v0
	s_and_b32 s9, s9, 4
	v_bitop3_b32 v2, v1, v131, 7 bitop3:0x6c
	v_lshlrev_b32_e32 v1, 11, v1
	s_or_b32 s9, s15, s9
	v_lshl_or_b32 v48, v2, 4, v1
	v_or_b32_e32 v1, s9, v147
	v_lshrrev_b32_e32 v0, 3, v0
	s_add_i32 s15, s8, 0x2000
	v_and_b32_e32 v56, 0xc0, v0
	v_lshlrev_b32_e32 v0, 11, v1
	v_or_b32_e32 v1, s15, v129
	s_ashr_i32 s15, s15, 8
	s_and_b32 s22, s15, 0x1ffff0
	s_lshr_b32 s15, s15, 1
	s_and_b32 s15, s15, 4
	s_add_i32 s73, s8, 0
	v_ashrrev_i32_e32 v2, 8, v1
	s_or_b32 s24, s22, s15
	s_add_i32 s15, s73, 0x4000
	s_mov_b32 m0, s73
	v_or3_b32 v0, v0, v56, v172
	v_bitop3_b32 v3, v2, v131, 7 bitop3:0x6c
	v_lshlrev_b32_e32 v2, 11, v2
	global_load_lds_dwordx4 v48, s[18:19]
	s_mov_b32 m0, s15
	v_lshl_or_b32 v50, v3, 4, v2
	v_or_b32_e32 v2, s24, v147
	v_lshrrev_b32_e32 v1, 3, v1
	global_load_lds_dwordx4 v0, s[16:17]
	s_add_i32 m0, s73, 0x2000
	v_and_b32_e32 v1, 0xc0, v1
	v_lshlrev_b32_e32 v2, 11, v2
	global_load_lds_dwordx4 v50, s[18:19]
	s_add_i32 m0, s73, 0x6000
	v_or3_b32 v1, v2, v1, v172
	s_add_u32 s22, s18, 0x20000
	global_load_lds_dwordx4 v1, s[16:17]
	s_addc_u32 s23, s19, 0
	s_add_i32 m0, s73, 0x8000
	s_add_u32 s26, s16, 0x20000
	s_addc_u32 s27, s17, 0
	s_add_i32 s15, s73, 0xc000
	global_load_lds_dwordx4 v48, s[22:23]
	s_mov_b32 m0, s15
	v_add_u32_e32 v4, 0, v179
	global_load_lds_dwordx4 v0, s[26:27]
	s_add_i32 m0, s73, 0xa000
	v_add_u32_e32 v8, 0, v182
	global_load_lds_dwordx4 v50, s[22:23]
	s_add_i32 m0, s73, 0xe000
	s_add_u32 s22, s18, 0x40000
	global_load_lds_dwordx4 v1, s[26:27]
	s_addc_u32 s23, s19, 0
	s_add_i32 m0, s73, 0x10000
	s_waitcnt vmcnt(4)
	s_add_u32 s26, s16, 0x40000
	s_waitcnt lgkmcnt(0)
	s_barrier
	s_addc_u32 s27, s17, 0
	s_add_i32 s15, s73, 0x14000
	global_load_lds_dwordx4 v48, s[22:23]
	s_mov_b32 m0, s15
	s_mov_b32 s36, s37
	global_load_lds_dwordx4 v0, s[26:27]
	s_add_i32 m0, s73, 0x12000
	s_mov_b32 s38, s37
	global_load_lds_dwordx4 v50, s[22:23]
	s_add_i32 m0, s73, 0x16000
	s_mov_b32 s39, s37
	global_load_lds_dwordx4 v1, s[26:27]
	ds_read_b128 v[0:3], v4
	ds_read_b128 v[4:7], v4 offset:8192
	s_waitcnt vmcnt(0) lgkmcnt(0)
	v_mfma_f32_32x32x16_bf16 v[32:47], v[4:7], v[108:111], 0
	v_add_u32_e32 v4, 0, v180
	s_mov_b32 s40, s37
	s_mov_b32 s41, s37
	s_mov_b32 s42, s37
	s_mov_b32 s43, s37
	s_mov_b32 s44, s37
	s_mov_b32 s45, s37
	v_mfma_f32_32x32x16_bf16 v[16:31], v[0:3], v[108:111], 0
	ds_read_b128 v[0:3], v4
	ds_read_b128 v[4:7], v4 offset:8192
	ds_read_b128 v[52:55], v8 offset:8192
	s_mov_b32 s46, s37
	s_mov_b32 s47, s37
	s_mov_b32 s48, s37
	s_mov_b32 s49, s37
	s_mov_b32 s50, s37
	s_waitcnt lgkmcnt(1)
	v_mfma_f32_32x32x16_bf16 v[32:47], v[4:7], v[104:107], v[32:47]
	v_add_u32_e32 v4, 0, v181
	s_mov_b32 s51, s37
	s_mov_b32 s15, s37
	v_mov_b32_e32 v49, v145
	v_mov_b32_e32 v51, v145
	s_mov_b32 s82, 4
	s_mov_b32 s83, 0x10000
	v_mfma_f32_32x32x16_bf16 v[16:31], v[0:3], v[104:107], v[16:31]
	ds_read_b128 v[0:3], v4
	ds_read_b128 v[4:7], v4 offset:8192
	v_lshl_add_u32 v156, v128, 2, s67
	v_mov_b32_e32 v157, 0
	s_waitcnt lgkmcnt(1)
	v_mfma_f32_32x32x16_bf16 v[16:31], v[0:3], v[100:103], v[16:31]
	ds_read_b128 v[0:3], v8
	s_waitcnt vmcnt(4)
	s_waitcnt lgkmcnt(0)
	s_barrier
; #define AWAIT(more) do { if (more) asm volatile("s_waitcnt vmcnt(4)" ::: "memory"); else asm volatile("s_waitcnt vmcnt(0)" ::: "memory"); } while (0)
; #define ABAR() do { asm volatile("s_waitcnt lgkmcnt(0)" ::: "memory"); __builtin_amdgcn_s_barrier(); asm volatile("" ::: "memory"); } while (0)
; __device__ __forceinline__ void partialSM(f32x16& p0, f32x16& p1, float& m_reg, float& mn, float& alpha, float C, float thr) {
;   float pmax = p0[0]; for (int r = 1; r < 16; ++r) pmax = fmaxf(pmax, p0[r]); for (int r = 0; r < 16; ++r) pmax = fmaxf(pmax, p1[r]);
;   { auto rr = __builtin_amdgcn_permlane32_swap(__float_as_uint(pmax), __float_as_uint(pmax), false, false);
;     pmax = fmaxf(__uint_as_float(rr[0]), __uint_as_float(rr[1])); }
;   if (__builtin_expect(__all(pmax - m_reg <= thr), 1)) { mn = m_reg; alpha = 1.f; }
;   else { mn = fmaxf(m_reg, pmax); alpha = __builtin_amdgcn_exp2f((m_reg - mn) * C); m_reg = mn; }
;   float mnC = -mn * C;
;   for (int r = 0; r < 16; ++r) p0[r] = fmaf(p0[r], C, mnC); for (int r = 0; r < 16; ++r) p1[r] = fmaf(p1[r], C, mnC);
;   for (int r = 0; r < 16; ++r) p0[r] = __builtin_amdgcn_exp2f(p0[r]);
; }
; template <int QH> __device__ __forceinline__ void attn_dense_body(const bf16_t* __restrict__ Qb, const bf16_t* __restrict__ Kh, const bf16_t* __restrict__ Vh,
;                                                 bf16_t* __restrict__ Ob, int seq, float scale, char* lds, const int tid) {
;     ...
;   qkt<QH>(pA0, pA1, KSLOT(0), qr, r32, hi); partialSM(pA0, pA1, m_reg, mnA, alA, C, thr);
;   AWAIT(2 < NT); ABAR();
;   for (int j = 1; j + 1 < NT; j += 2) {
;     if (j + 2 < NT) ADMA(j + 2);
	s_waitcnt lgkmcnt(1)
	v_mfma_f32_32x32x16_bf16 v[32:47], v[4:7], v[100:103], v[32:47]
	s_waitcnt lgkmcnt(0)
	v_mfma_f32_32x32x16_bf16 v[16:31], v[0:3], v[96:99], v[16:31]
	v_mov_b64_e32 v[0:1], s[36:37]
	v_mov_b64_e32 v[2:3], s[38:39]
	v_mov_b64_e32 v[4:5], s[40:41]
	v_mov_b64_e32 v[6:7], s[42:43]
	v_mov_b64_e32 v[8:9], s[44:45]
	v_mov_b64_e32 v[10:11], s[46:47]
	v_mov_b64_e32 v[12:13], s[48:49]
	v_mfma_f32_32x32x16_bf16 v[32:47], v[52:55], v[96:99], v[32:47]
	s_nop 3
	v_max_f32_e32 v52, v17, v17
	v_max_f32_e32 v53, v16, v16
	v_max_f32_e32 v52, v53, v52
	v_max3_f32 v52, v52, v18, v19
	v_max3_f32 v52, v52, v20, v21
	v_max3_f32 v52, v52, v22, v23
	v_max3_f32 v52, v52, v24, v25
	v_max3_f32 v52, v52, v26, v27
	v_max3_f32 v52, v52, v28, v29
	v_max3_f32 v52, v52, v30, v31
	v_max3_f32 v52, v52, v32, v33
	v_max3_f32 v52, v52, v34, v35
	v_max3_f32 v52, v52, v36, v37
	v_max3_f32 v52, v52, v38, v39
	v_max3_f32 v52, v52, v40, v41
	v_max3_f32 v52, v52, v42, v43
	v_max3_f32 v52, v52, v44, v45
	v_max3_f32 v52, v52, v46, v47
	v_mov_b32_e32 v53, v52
	s_nop 1
	v_permlane32_swap_b32_e32 v52, v53
	v_max_f32_e32 v53, v53, v53
	v_max_f32_e32 v52, v52, v52
	v_max_f32_e32 v52, v52, v53
	v_mov_b64_e32 v[14:15], s[50:51]
	v_add_f32_e32 v53, 0x7149f2ca, v52
	s_mov_b32 s40, 0x41000000
	v_cmp_ge_f32_e32 vcc, s40, v53
	s_cmp_eq_u64 vcc, exec
	v_max_f32_e32 v52, 0xf149f2ca, v52
	s_cselect_b64 vcc, -1, 0
	v_cndmask_b32_e32 v158, v52, v197, vcc
	v_sub_f32_e32 v53, 0xf149f2ca, v52
	v_mul_f32_e32 v52, 0xbfb8aa3b, v158
	v_fmamk_f32 v16, v16, 0x3fb8aa3b, v52
	v_exp_f32_e32 v162, v16
	v_fmamk_f32 v16, v17, 0x3fb8aa3b, v52
	v_exp_f32_e32 v164, v16
	v_fmamk_f32 v16, v18, 0x3fb8aa3b, v52
	v_exp_f32_e32 v166, v16
	v_fmamk_f32 v16, v19, 0x3fb8aa3b, v52
	v_exp_f32_e32 v168, v16
	v_fmamk_f32 v16, v20, 0x3fb8aa3b, v52
	v_exp_f32_e32 v170, v16
	v_fmamk_f32 v16, v21, 0x3fb8aa3b, v52
	v_exp_f32_e32 v184, v16
	v_fmamk_f32 v16, v22, 0x3fb8aa3b, v52
	v_exp_f32_e32 v185, v16
	v_fmamk_f32 v16, v23, 0x3fb8aa3b, v52
	v_exp_f32_e32 v200, v16
	v_fmamk_f32 v16, v24, 0x3fb8aa3b, v52
	v_exp_f32_e32 v160, v16
	v_fmamk_f32 v16, v25, 0x3fb8aa3b, v52
	v_exp_f32_e32 v161, v16
	v_fmamk_f32 v16, v26, 0x3fb8aa3b, v52
	v_mul_f32_e32 v53, 0x3fb8aa3b, v53
	v_exp_f32_e32 v163, v16
	v_fmamk_f32 v16, v27, 0x3fb8aa3b, v52
	v_exp_f32_e32 v53, v53
	v_exp_f32_e32 v165, v16
	v_fmamk_f32 v16, v28, 0x3fb8aa3b, v52
	v_exp_f32_e32 v167, v16
	v_fmamk_f32 v16, v29, 0x3fb8aa3b, v52
	v_add_u32_e32 v17, s8, v183
	v_exp_f32_e32 v169, v16
	v_fmamk_f32 v16, v30, 0x3fb8aa3b, v52
	s_lshl_b64 s[22:23], s[14:15], 8
	v_lshrrev_b32_e32 v17, 3, v17
	v_exp_f32_e32 v171, v16
	v_add_lshl_u32 v16, s24, v147, 11
	v_and_b32_e32 v17, 0xc0, v17
	s_add_u32 s24, s61, s72
	v_pk_fma_f32 v[134:135], v[46:47], s[4:5], v[52:53] op_sel_hi:[1,0,0]
	v_pk_fma_f32 v[136:137], v[44:45], s[4:5], v[52:53] op_sel_hi:[1,0,0]
	v_pk_fma_f32 v[138:139], v[42:43], s[4:5], v[52:53] op_sel_hi:[1,0,0]
	v_pk_fma_f32 v[140:141], v[40:41], s[4:5], v[52:53] op_sel_hi:[1,0,0]
	v_pk_fma_f32 v[142:143], v[38:39], s[4:5], v[52:53] op_sel_hi:[1,0,0]
	v_pk_fma_f32 v[150:151], v[36:37], s[4:5], v[52:53] op_sel_hi:[1,0,0]
	v_pk_fma_f32 v[152:153], v[34:35], s[4:5], v[52:53] op_sel_hi:[1,0,0]
	v_pk_fma_f32 v[154:155], v[32:33], s[4:5], v[52:53] op_sel_hi:[1,0,0]
	v_fmac_f32_e32 v52, 0x3fb8aa3b, v31
	v_or3_b32 v16, v172, v16, v17
	v_mov_b32_e32 v17, v145
	s_addc_u32 s25, s62, s71
	v_exp_f32_e32 v199, v52
	v_mov_b32_e32 v112, v16
	v_mov_b32_e32 v113, s24
	v_add_lshl_u32 v16, s9, v147, 11
	s_add_u32 s8, s63, s72
	v_or3_b32 v16, v172, v16, v56
	s_addc_u32 s9, s64, s71
	v_cndmask_b32_e64 v159, v53, 1.0, vcc
	v_mov_b32_e32 v114, v16
	v_mov_b32_e32 v115, s25
	v_mov_b32_e32 v116, v50
	v_mov_b32_e32 v117, s8
	v_mov_b32_e32 v118, v48
	v_mov_b32_e32 v119, s9
	v_mov_b64_e32 v[62:63], v[14:15]
	v_mov_b64_e32 v[46:47], v[14:15]
	v_mov_b64_e32 v[30:31], v[14:15]
	s_movk_i32 s44, 0x1000
	v_mov_b64_e32 v[60:61], v[12:13]
	v_mov_b64_e32 v[58:59], v[10:11]
	v_mov_b64_e32 v[56:57], v[8:9]
	v_mov_b64_e32 v[54:55], v[6:7]
	v_mov_b64_e32 v[52:53], v[4:5]
	v_mov_b64_e32 v[50:51], v[2:3]
	v_mov_b64_e32 v[48:49], v[0:1]
	v_mov_b64_e32 v[44:45], v[12:13]
	v_mov_b64_e32 v[42:43], v[10:11]
	v_mov_b64_e32 v[40:41], v[8:9]
	v_mov_b64_e32 v[38:39], v[6:7]
	v_mov_b64_e32 v[36:37], v[4:5]
	v_mov_b64_e32 v[34:35], v[2:3]
	v_mov_b64_e32 v[32:33], v[0:1]
	v_mov_b64_e32 v[28:29], v[12:13]
	v_mov_b64_e32 v[26:27], v[10:11]
	v_mov_b64_e32 v[24:25], v[8:9]
	v_mov_b64_e32 v[22:23], v[6:7]
	v_mov_b64_e32 v[20:21], v[4:5]
	v_mov_b64_e32 v[18:19], v[2:3]
	v_mov_b64_e32 v[16:17], v[0:1]
	v_readfirstlane_b32 s46, v113
	v_readfirstlane_b32 s47, v115
	v_readfirstlane_b32 s42, v117
	v_readfirstlane_b32 s43, v119
	s_add_u32 s46, s46, s22
	s_addc_u32 s47, s47, s23
	s_add_u32 s46, s46, 0x9dc9000
	s_addc_u32 s47, s47, 0
	s_add_u32 s42, s42, s22
	s_addc_u32 s43, s43, s23
	s_add_u32 s42, s42, 0x9dc9000
	s_addc_u32 s43, s43, 0
.LBB0_130:
	s_add_i32 s8, s82, -1
	s_cmp_ge_u32 s8, s70
	s_cselect_b64 s[24:25], -1, 0
	s_and_b64 vcc, exec, s[24:25]
	s_cbranch_vccnz .LBB0_132
	s_add_i32 s8, s83, 0x8000
	s_and_b32 s8, s8, 0x18000
	s_add_i32 s8, s73, s8
	s_add_i32 s9, s8, 0x4000
	s_mov_b32 m0, s8
	s_nop 0
	global_load_lds_dwordx4 v118, s[42:43]
	s_mov_b32 m0, s9
	s_nop 0
	global_load_lds_dwordx4 v114, s[46:47]
	s_add_i32 m0, s8, 0x2000
	s_nop 0
	global_load_lds_dwordx4 v116, s[42:43]
	s_add_i32 m0, s8, 0x6000
	s_nop 0
	global_load_lds_dwordx4 v112, s[46:47]

; #define SBAR() __builtin_amdgcn_sched_barrier(0)
; template <int QH> __device__ __forceinline__ void attn_dense_body(const bf16_t* __restrict__ Qb, const bf16_t* __restrict__ Kh, const bf16_t* __restrict__ Vh,
;                                                 bf16_t* __restrict__ Ob, int seq, float scale, char* lds, const int tid) {
;     ...
;     if (j + 3 < NT) ADMA(j + 3);
;     SBAR(); qkt<QH>(pA0, pA1, KSLOT(j + 1), qr, r32, hi);
.LBB0_140:
	s_cmp_ge_u32 s82, s70
	s_cselect_b64 s[24:25], -1, 0
	s_and_b64 vcc, exec, s[24:25]
	s_cbranch_vccnz .LBB0_142
	s_add_i32 s26, s73, s38
	s_add_i32 s27, s26, 0x4000
	s_add_u32 s42, s42, 0x20000
	s_addc_u32 s43, s43, 0
	s_add_u32 s46, s46, 0x20000
	s_addc_u32 s47, s47, 0
	s_mov_b32 m0, s26
	s_nop 0
	global_load_lds_dwordx4 v118, s[42:43]
	s_mov_b32 m0, s27
	s_nop 0
	global_load_lds_dwordx4 v114, s[46:47]
	s_add_i32 m0, s26, 0x2000
	s_nop 0
	global_load_lds_dwordx4 v116, s[42:43]
	s_add_i32 m0, s26, 0x6000
	s_nop 0
	global_load_lds_dwordx4 v112, s[46:47]
	s_sub_u32 s42, s42, 0x20000
	s_subb_u32 s43, s43, 0
	s_sub_u32 s46, s46, 0x20000
	s_subb_u32 s47, s47, 0

; #define AWAIT(more) do { if (more) asm volatile("s_waitcnt vmcnt(4)" ::: "memory"); else asm volatile("s_waitcnt vmcnt(0)" ::: "memory"); } while (0)
; #define ABAR() do { asm volatile("s_waitcnt lgkmcnt(0)" ::: "memory"); __builtin_amdgcn_s_barrier(); asm volatile("" ::: "memory"); } while (0)
; #define RESC(a) do { if (__any((a) < 1.f)) { if (hi == 0) al_l[r32] = (a); asm volatile("s_waitcnt lgkmcnt(0)" ::: "memory"); \
;     for (int d = 0; d < 4; ++d) for (int r = 0; r < 16; ++r) o[d][r] *= al_l[crow(r, hi)]; } } while (0)
; __device__ __forceinline__ void partialSM(f32x16& p0, f32x16& p1, float& m_reg, float& mn, float& alpha, float C, float thr) {
;     ...
;     pmax = fmaxf(__uint_as_float(rr[0]), __uint_as_float(rr[1])); }
;   if (__builtin_expect(__all(pmax - m_reg <= thr), 1)) { mn = m_reg; alpha = 1.f; }
;   else { mn = fmaxf(m_reg, pmax); alpha = __builtin_amdgcn_exp2f((m_reg - mn) * C); m_reg = mn; }
;   float mnC = -mn * C;
;   for (int r = 0; r < 16; ++r) p0[r] = fmaf(p0[r], C, mnC); for (int r = 0; r < 16; ++r) p1[r] = fmaf(p1[r], C, mnC);
;   for (int r = 0; r < 16; ++r) p0[r] = __builtin_amdgcn_exp2f(p0[r]);
; }
; __device__ __forceinline__ void finishSM(f32x16& p0, f32x16& p1, float alpha, float& l_reg, bf16x8& pa0, bf16x8& pa1, bf16x8& pa2, bf16x8& pa3) {
;   for (int r = 0; r < 16; ++r) p1[r] = __builtin_amdgcn_exp2f(p1[r]);
;   float ps = 0; for (int r = 0; r < 16; ++r) ps += p0[r]; for (int r = 0; r < 16; ++r) ps += p1[r];
;   { auto rr = __builtin_amdgcn_permlane32_swap(__float_as_uint(ps), __float_as_uint(ps), false, false);
;     ps = __uint_as_float(rr[0]) + __uint_as_float(rr[1]); }
;   l_reg = l_reg * alpha + ps;
; template <int QH> __device__ __forceinline__ void attn_dense_body(const bf16_t* __restrict__ Qb, const bf16_t* __restrict__ Kh, const bf16_t* __restrict__ Vh,
;                                                 bf16_t* __restrict__ Ob, int seq, float scale, char* lds, const int tid) {
;     ...
;     pv_d0(o, VSLOT(j), pa0, pa1, pa2, pa3); partialSM(pA0, pA1, m_reg, mnA, alA, C, thr);
;     AWAIT(j + 3 < NT); ABAR();
;     RESC(alA);
;   }
.LBB0_150:
	v_add_f32_e32 v125, v134, v135
	v_cndmask_b32_e64 v158, v124, v121, s[8:9]
	v_fmac_f32_e32 v125, v159, v157
	v_add_f32_e32 v157, v122, v123
	v_mul_f32_e32 v122, 0xbfb8aa3b, v158
	v_mov_b32_e32 v121, v122
	v_fmamk_f32 v80, v80, 0x3fb8aa3b, v122
	v_fmamk_f32 v81, v81, 0x3fb8aa3b, v122
	v_fmamk_f32 v82, v82, 0x3fb8aa3b, v122
	v_fmamk_f32 v83, v83, 0x3fb8aa3b, v122
	v_fmamk_f32 v84, v84, 0x3fb8aa3b, v122
	v_fmamk_f32 v85, v85, 0x3fb8aa3b, v122
	v_fmamk_f32 v86, v86, 0x3fb8aa3b, v122
	v_fmamk_f32 v87, v87, 0x3fb8aa3b, v122
	v_fmamk_f32 v88, v88, 0x3fb8aa3b, v122
	v_fmamk_f32 v89, v89, 0x3fb8aa3b, v122
	v_fmamk_f32 v90, v90, 0x3fb8aa3b, v122
	v_fmamk_f32 v91, v91, 0x3fb8aa3b, v122
	v_fmamk_f32 v92, v92, 0x3fb8aa3b, v122
	v_fmamk_f32 v93, v93, 0x3fb8aa3b, v122
	v_fmamk_f32 v94, v94, 0x3fb8aa3b, v122
	v_fmac_f32_e32 v121, 0x3fb8aa3b, v95
	v_exp_f32_e32 v162, v80
	v_exp_f32_e32 v164, v81
	v_exp_f32_e32 v166, v82
	v_exp_f32_e32 v168, v83
	v_exp_f32_e32 v170, v84
	v_exp_f32_e32 v184, v85
	v_exp_f32_e32 v185, v86
	v_exp_f32_e32 v200, v87
	v_exp_f32_e32 v160, v88
	v_exp_f32_e32 v161, v89
	v_exp_f32_e32 v163, v90
	v_exp_f32_e32 v165, v91
	v_exp_f32_e32 v167, v92
	v_exp_f32_e32 v169, v93
	v_exp_f32_e32 v171, v94
	v_exp_f32_e32 v199, v121
	v_fmac_f32_e32 v157, v125, v136
	v_pk_fma_f32 v[154:155], v[64:65], s[4:5], v[122:123] op_sel_hi:[1,0,0]
	v_pk_fma_f32 v[152:153], v[66:67], s[4:5], v[122:123] op_sel_hi:[1,0,0]
	v_pk_fma_f32 v[150:151], v[68:69], s[4:5], v[122:123] op_sel_hi:[1,0,0]
	v_pk_fma_f32 v[142:143], v[70:71], s[4:5], v[122:123] op_sel_hi:[1,0,0]
	v_pk_fma_f32 v[140:141], v[72:73], s[4:5], v[122:123] op_sel_hi:[1,0,0]
	v_pk_fma_f32 v[138:139], v[74:75], s[4:5], v[122:123] op_sel_hi:[1,0,0]
	v_pk_fma_f32 v[136:137], v[76:77], s[4:5], v[122:123] op_sel_hi:[1,0,0]
	v_pk_fma_f32 v[134:135], v[78:79], s[4:5], v[122:123] op_sel_hi:[1,0,0]
	s_add_u32 s42, s42, s74
	s_addc_u32 s43, s43, s75
	s_add_u32 s46, s46, s74
	s_addc_u32 s47, s47, s75
	s_add_i32 s82, s82, 2
	s_and_b64 vcc, exec, s[24:25]
	s_cbranch_vccnz .LBB0_152
	s_mov_b32 s83, s15
	v_mov_b32_e32 v159, v120
	s_branch .LBB0_130

; #define LAS __attribute__((address_space(3)))
; __device__ __forceinline__ int v_rd_base(int lane) { return ((lane & 3) << 3) | (((lane >> 2) & 3) << 6) | (((lane >> 4) & 1) << 5) | (((lane >> 5) & 1) << 8); }
; #define AWAIT(more) do { if (more) asm volatile("s_waitcnt vmcnt(4)" ::: "memory"); else asm volatile("s_waitcnt vmcnt(0)" ::: "memory"); } while (0)
; #define ABAR() do { asm volatile("s_waitcnt lgkmcnt(0)" ::: "memory"); __builtin_amdgcn_s_barrier(); asm volatile("" ::: "memory"); } while (0)
; template <int QH> __device__ __forceinline__ void attn_dense_body(const bf16_t* __restrict__ Qb, const bf16_t* __restrict__ Kh, const bf16_t* __restrict__ Vh,
;                                                 bf16_t* __restrict__ Ob, int seq, float scale, char* lds, const int tid) {
;     ...
;   const int wid = __builtin_amdgcn_readfirstlane(tid >> 6), lane = tid & 63, r32 = lane & 31, hi = lane >> 5;
;   LAS unsigned char* L3 = (LAS unsigned char*)lds;
;   float* ws = (float*)(lds + 4 * SLOT) + wid * 64; float* li_l = ws; float* al_l = ws + 32;
;   float m_reg = -1e30f, l_reg = 0; f32x16 o[4] = {}; bf16x8 qr[8];
;   const bf16_t* Qw = Qb + (long)(wid * QBLK + r32) * LDQ + hi * 8;
; #pragma unroll
;   for (int d0 = 0; d0 < 8; ++d0) qr[d0] = *reinterpret_cast<const bf16x8*>(Qw + d0 * 16);
;   unsigned ko[2], vo[2];
; #pragma unroll
;   for (int n = 0; n < 2; ++n) { const int d = (n * 8 + wid) * 1024 + lane * 16;
;     { const int r = d >> 8, pos = (d & 255) >> 4, c = pos ^ (r & 7); ko[n] = (unsigned)(r * LDK + c * 8) * 2u; }
;     { const int sb = d >> 9, e = d & 511, kk = (sb >> 2) * 8 + (e >> 6), k = (kk & ~0xC) | ((kk & 4) << 1) | ((kk & 8) >> 1), c = (sb & 3) * 32 + ((e & 63) >> 1); vo[n] = (unsigned)(k * LDK + c) * 2u; } }
;   const int vrb = (int)(uintptr_t)lds + 16384 + v_rd_base(lane);
;     ...
;   f32x16 pA0, pA1, pB0, pB1; float mnA, mnB, alA, alB; bf16x8 pa0, pa1, pa2, pa3; const int NT = seq / KVBLK;
;   ADMA(0); ADMA(1);
;   asm volatile("s_waitcnt vmcnt(4)" ::: "memory"); ABAR();
;   if (2 < NT) ADMA(2);
;   qkt<QH>(pA0, pA1, KSLOT(0), qr, r32, hi); partialSM(pA0, pA1, m_reg, mnA, alA, C, thr);
;   AWAIT(2 < NT); ABAR();
.LBB0_159:
	s_and_b64 vcc, exec, s[8:9]
	s_cbranch_vccz .LBB0_86
	v_readfirstlane_b32 s8, v146
	s_ashr_i32 s9, s8, 6
	s_lshl_b32 s10, s9, 5
	v_or_b32_e32 v0, s10, v128
	v_ashrrev_i32_e32 v1, 31, v0
	v_lshlrev_b64 v[0:1], 12, v[0:1]
	v_lshl_add_u64 v[0:1], s[20:21], 0, v[0:1]
	v_lshl_add_u64 v[0:1], v[0:1], 0, v[144:145]
	flat_load_dwordx4 v[108:111], v[0:1]
	flat_load_dwordx4 v[104:107], v[0:1] offset:32
	flat_load_dwordx4 v[100:103], v[0:1] offset:64
	flat_load_dwordx4 v[96:99], v[0:1] offset:96
	s_and_b32 s8, s8, 0x3fffffc0
	s_lshl_b32 s8, s8, 2
	s_add_i32 s8, s8, 0
	s_add_i32 s67, s8, 0x20000
	s_lshl_b32 s8, s9, 10
	s_ashr_i32 s9, s8, 8
	v_or_b32_e32 v0, s8, v129
	s_and_b32 s15, s9, 0x1ffff0
	s_lshr_b32 s9, s9, 1
	v_ashrrev_i32_e32 v1, 8, v0
	s_and_b32 s9, s9, 4
	v_bitop3_b32 v2, v1, v131, 7 bitop3:0x6c
	v_lshlrev_b32_e32 v1, 11, v1
	s_or_b32 s9, s15, s9
	v_lshl_or_b32 v144, v2, 4, v1
	v_or_b32_e32 v1, s9, v147
	v_lshrrev_b32_e32 v0, 3, v0
	s_add_i32 s15, s8, 0x2000
	v_and_b32_e32 v54, 0xc0, v0
	v_lshlrev_b32_e32 v0, 11, v1
	v_or_b32_e32 v1, s15, v129
	s_ashr_i32 s15, s15, 8
	s_and_b32 s20, s15, 0x1ffff0
	s_lshr_b32 s15, s15, 1
	s_and_b32 s15, s15, 4
	s_or_b32 s22, s20, s15
	s_add_i32 s20, s8, 0
	v_ashrrev_i32_e32 v2, 8, v1
	s_add_i32 s15, s20, 0x4000
	s_mov_b32 m0, s20
	v_or3_b32 v0, v0, v54, v172
	v_bitop3_b32 v3, v2, v131, 7 bitop3:0x6c
	v_lshlrev_b32_e32 v2, 11, v2
	global_load_lds_dwordx4 v144, s[18:19]
	s_mov_b32 m0, s15
	v_lshl_or_b32 v48, v3, 4, v2
	v_or_b32_e32 v2, s22, v147
	v_lshrrev_b32_e32 v1, 3, v1
	global_load_lds_dwordx4 v0, s[16:17]
	s_add_i32 m0, s20, 0x2000
	v_and_b32_e32 v1, 0xc0, v1
	v_lshlrev_b32_e32 v2, 11, v2
	global_load_lds_dwordx4 v48, s[18:19]
	s_add_i32 m0, s20, 0x6000
	v_or3_b32 v1, v2, v1, v172
	s_add_u32 s24, s18, 0x20000
	global_load_lds_dwordx4 v1, s[16:17]
	s_addc_u32 s25, s19, 0
	s_add_i32 m0, s20, 0x8000
	s_add_u32 s26, s16, 0x20000
	s_addc_u32 s27, s17, 0
	s_add_i32 s15, s20, 0xc000
	global_load_lds_dwordx4 v144, s[24:25]
	s_mov_b32 m0, s15
	v_add_u32_e32 v4, 0, v175
	global_load_lds_dwordx4 v0, s[26:27]
	s_add_i32 m0, s20, 0xa000
	v_add_u32_e32 v8, 0, v178
	global_load_lds_dwordx4 v48, s[24:25]
	s_add_i32 m0, s20, 0xe000
	s_add_u32 s18, s18, 0x40000
	global_load_lds_dwordx4 v1, s[26:27]
	s_addc_u32 s19, s19, 0
	s_add_i32 m0, s20, 0x10000
	s_waitcnt vmcnt(4)
	s_add_u32 s16, s16, 0x40000
	s_waitcnt lgkmcnt(0)
	s_barrier
	s_addc_u32 s17, s17, 0
	s_add_i32 s15, s20, 0x14000
	global_load_lds_dwordx4 v144, s[18:19]
	s_mov_b32 m0, s15
	s_mov_b32 s26, 0x41000000
	global_load_lds_dwordx4 v0, s[16:17]
	s_add_i32 m0, s20, 0x12000
	s_mov_b32 s15, s37
	global_load_lds_dwordx4 v48, s[18:19]
	s_add_i32 m0, s20, 0x16000
	s_mov_b32 s36, s37
	global_load_lds_dwordx4 v1, s[16:17]
	ds_read_b128 v[0:3], v4
	ds_read_b128 v[4:7], v4 offset:8192
	s_waitcnt vmcnt(0) lgkmcnt(0)
	v_mfma_f32_32x32x16_bf16 v[32:47], v[4:7], v[108:111], 0
	v_add_u32_e32 v4, 0, v176
	s_mov_b32 s38, s37
	s_mov_b32 s39, s37
	s_mov_b32 s40, s37
	s_mov_b32 s41, s37
	s_mov_b32 s42, s37
	s_mov_b32 s43, s37
	v_mfma_f32_32x32x16_bf16 v[16:31], v[0:3], v[108:111], 0
	ds_read_b128 v[0:3], v4
	ds_read_b128 v[4:7], v4 offset:8192
	ds_read_b128 v[50:53], v8 offset:8192
	s_mov_b32 s44, s37
	s_mov_b32 s45, s37
	s_mov_b32 s46, s37
	s_mov_b32 s47, s37
	s_mov_b32 s48, s37
	s_waitcnt lgkmcnt(1)
	v_mfma_f32_32x32x16_bf16 v[32:47], v[4:7], v[104:107], v[32:47]
	v_add_u32_e32 v4, 0, v177
	s_mov_b32 s49, s37
	s_mov_b32 s50, s37
	s_mov_b32 s51, s37
	v_mov_b32_e32 v49, v145
	s_mov_b32 s21, 4
	s_mov_b32 s23, 0x10000
	v_mfma_f32_32x32x16_bf16 v[16:31], v[0:3], v[104:107], v[16:31]
	ds_read_b128 v[0:3], v4
	ds_read_b128 v[4:7], v4 offset:8192
	v_lshl_add_u32 v156, v128, 2, s67
	s_waitcnt lgkmcnt(1)
	v_mfma_f32_32x32x16_bf16 v[16:31], v[0:3], v[100:103], v[16:31]
	ds_read_b128 v[0:3], v8
	s_waitcnt vmcnt(4)
	s_waitcnt lgkmcnt(0)
	s_barrier
; #define AWAIT(more) do { if (more) asm volatile("s_waitcnt vmcnt(4)" ::: "memory"); else asm volatile("s_waitcnt vmcnt(0)" ::: "memory"); } while (0)
; #define ABAR() do { asm volatile("s_waitcnt lgkmcnt(0)" ::: "memory"); __builtin_amdgcn_s_barrier(); asm volatile("" ::: "memory"); } while (0)
; __device__ __forceinline__ void partialSM(f32x16& p0, f32x16& p1, float& m_reg, float& mn, float& alpha, float C, float thr) {
;   float pmax = p0[0]; for (int r = 1; r < 16; ++r) pmax = fmaxf(pmax, p0[r]); for (int r = 0; r < 16; ++r) pmax = fmaxf(pmax, p1[r]);
;   { auto rr = __builtin_amdgcn_permlane32_swap(__float_as_uint(pmax), __float_as_uint(pmax), false, false);
;     pmax = fmaxf(__uint_as_float(rr[0]), __uint_as_float(rr[1])); }
;   if (__builtin_expect(__all(pmax - m_reg <= thr), 1)) { mn = m_reg; alpha = 1.f; }
;   else { mn = fmaxf(m_reg, pmax); alpha = __builtin_amdgcn_exp2f((m_reg - mn) * C); m_reg = mn; }
;   float mnC = -mn * C;
;   for (int r = 0; r < 16; ++r) p0[r] = fmaf(p0[r], C, mnC); for (int r = 0; r < 16; ++r) p1[r] = fmaf(p1[r], C, mnC);
;   for (int r = 0; r < 16; ++r) p0[r] = __builtin_amdgcn_exp2f(p0[r]);
; }
; template <int QH> __device__ __forceinline__ void attn_dense_body(const bf16_t* __restrict__ Qb, const bf16_t* __restrict__ Kh, const bf16_t* __restrict__ Vh,
;                                                 bf16_t* __restrict__ Ob, int seq, float scale, char* lds, const int tid) {
;     ...
;   qkt<QH>(pA0, pA1, KSLOT(0), qr, r32, hi); partialSM(pA0, pA1, m_reg, mnA, alA, C, thr);
;   AWAIT(2 < NT); ABAR();
;   for (int j = 1; j + 1 < NT; j += 2) {
;     if (j + 2 < NT) ADMA(j + 2);
	s_waitcnt lgkmcnt(1)
	v_mfma_f32_32x32x16_bf16 v[32:47], v[4:7], v[100:103], v[32:47]
	s_waitcnt lgkmcnt(0)
	v_mfma_f32_32x32x16_bf16 v[16:31], v[0:3], v[96:99], v[16:31]
	v_mov_b64_e32 v[0:1], s[36:37]
	v_mov_b64_e32 v[14:15], s[50:51]
	v_mov_b64_e32 v[2:3], s[38:39]
	v_mov_b64_e32 v[4:5], s[40:41]
	v_mov_b64_e32 v[6:7], s[42:43]
	v_mov_b64_e32 v[8:9], s[44:45]
	v_mov_b64_e32 v[10:11], s[46:47]
	v_mfma_f32_32x32x16_bf16 v[32:47], v[50:53], v[96:99], v[32:47]
	s_nop 3
	v_max_f32_e32 v50, v17, v17
	v_max_f32_e32 v51, v16, v16
	v_max_f32_e32 v50, v51, v50
	v_max3_f32 v50, v50, v18, v19
	v_max3_f32 v50, v50, v20, v21
	v_max3_f32 v50, v50, v22, v23
	v_max3_f32 v50, v50, v24, v25
	v_max3_f32 v50, v50, v26, v27
	v_max3_f32 v50, v50, v28, v29
	v_max3_f32 v50, v50, v30, v31
	v_max3_f32 v50, v50, v32, v33
	v_max3_f32 v50, v50, v34, v35
	v_max3_f32 v50, v50, v36, v37
	v_max3_f32 v50, v50, v38, v39
	v_max3_f32 v50, v50, v40, v41
	v_max3_f32 v50, v50, v42, v43
	v_max3_f32 v50, v50, v44, v45
	v_max3_f32 v50, v50, v46, v47
	v_mov_b32_e32 v51, v50
	s_nop 1
	v_permlane32_swap_b32_e32 v50, v51
	v_max_f32_e32 v51, v51, v51
	v_max_f32_e32 v50, v50, v50
	v_max_f32_e32 v50, v50, v51
	v_add_f32_e32 v51, 0x7149f2ca, v50
	v_cmp_ge_f32_e32 vcc, s26, v51
	s_cmp_eq_u64 vcc, exec
	v_max_f32_e32 v50, 0xf149f2ca, v50
	s_cselect_b64 vcc, -1, 0
	v_cndmask_b32_e32 v157, v50, v197, vcc
	v_sub_f32_e32 v51, 0xf149f2ca, v50
	v_mul_f32_e32 v50, 0xbfb8aa3b, v157
	v_fmamk_f32 v16, v16, 0x3fb8aa3b, v50
	v_exp_f32_e32 v161, v16
	v_fmamk_f32 v16, v17, 0x3fb8aa3b, v50
	v_exp_f32_e32 v163, v16
	v_fmamk_f32 v16, v18, 0x3fb8aa3b, v50
	v_exp_f32_e32 v165, v16
	v_fmamk_f32 v16, v19, 0x3fb8aa3b, v50
	v_exp_f32_e32 v167, v16
	v_fmamk_f32 v16, v20, 0x3fb8aa3b, v50
	v_exp_f32_e32 v169, v16
	v_fmamk_f32 v16, v21, 0x3fb8aa3b, v50
	v_exp_f32_e32 v171, v16
	v_fmamk_f32 v16, v22, 0x3fb8aa3b, v50
	v_exp_f32_e32 v184, v16
	v_fmamk_f32 v16, v23, 0x3fb8aa3b, v50
	v_exp_f32_e32 v199, v16
	v_fmamk_f32 v16, v24, 0x3fb8aa3b, v50
	v_exp_f32_e32 v159, v16
	v_fmamk_f32 v16, v25, 0x3fb8aa3b, v50
	v_exp_f32_e32 v160, v16
	v_fmamk_f32 v16, v26, 0x3fb8aa3b, v50
	v_mul_f32_e32 v51, 0x3fb8aa3b, v51
	v_exp_f32_e32 v162, v16
	v_fmamk_f32 v16, v27, 0x3fb8aa3b, v50
	v_exp_f32_e32 v51, v51
	v_exp_f32_e32 v164, v16
	v_fmamk_f32 v16, v28, 0x3fb8aa3b, v50
	v_exp_f32_e32 v166, v16
	v_fmamk_f32 v16, v29, 0x3fb8aa3b, v50
	v_add_u32_e32 v17, s8, v183
	v_exp_f32_e32 v168, v16
	v_fmamk_f32 v16, v30, 0x3fb8aa3b, v50
	s_lshl_b64 s[14:15], s[14:15], 8
	v_lshrrev_b32_e32 v17, 3, v17
	v_exp_f32_e32 v170, v16
	v_add_lshl_u32 v16, s22, v147, 11
	v_and_b32_e32 v17, 0xc0, v17
	s_add_u32 s16, s61, s72
	v_pk_fma_f32 v[134:135], v[46:47], s[4:5], v[50:51] op_sel_hi:[1,0,0]
	v_pk_fma_f32 v[136:137], v[44:45], s[4:5], v[50:51] op_sel_hi:[1,0,0]
	v_pk_fma_f32 v[138:139], v[42:43], s[4:5], v[50:51] op_sel_hi:[1,0,0]
	v_pk_fma_f32 v[140:141], v[40:41], s[4:5], v[50:51] op_sel_hi:[1,0,0]
	v_pk_fma_f32 v[142:143], v[38:39], s[4:5], v[50:51] op_sel_hi:[1,0,0]
	v_pk_fma_f32 v[150:151], v[36:37], s[4:5], v[50:51] op_sel_hi:[1,0,0]
	v_pk_fma_f32 v[152:153], v[34:35], s[4:5], v[50:51] op_sel_hi:[1,0,0]
	v_pk_fma_f32 v[154:155], v[32:33], s[4:5], v[50:51] op_sel_hi:[1,0,0]
	v_fmac_f32_e32 v50, 0x3fb8aa3b, v31
	v_or3_b32 v16, v172, v16, v17
	v_mov_b32_e32 v17, v145
	s_addc_u32 s17, s62, s71
	v_exp_f32_e32 v185, v50
	v_mov_b32_e32 v112, v16
	v_mov_b32_e32 v113, s16
	v_add_lshl_u32 v16, s9, v147, 11
	s_add_u32 s8, s63, s72
	v_or3_b32 v16, v172, v16, v54
	s_addc_u32 s9, s64, s71
	v_mov_b64_e32 v[12:13], s[48:49]
	v_cndmask_b32_e64 v158, v51, 1.0, vcc
	v_mov_b32_e32 v114, v16
	v_mov_b32_e32 v115, s17
	v_mov_b32_e32 v116, v48
	v_mov_b32_e32 v117, s8
	v_mov_b64_e32 v[62:63], v[14:15]
	v_mov_b64_e32 v[46:47], v[14:15]
	v_mov_b64_e32 v[30:31], v[14:15]
	s_movk_i32 s44, 0x1000
	v_mov_b32_e32 v118, v144
	v_mov_b32_e32 v119, s9
	v_mov_b32_e32 v144, 0
	v_mov_b64_e32 v[60:61], v[12:13]
	v_mov_b64_e32 v[58:59], v[10:11]
	v_mov_b64_e32 v[56:57], v[8:9]
	v_mov_b64_e32 v[54:55], v[6:7]
	v_mov_b64_e32 v[52:53], v[4:5]
	v_mov_b64_e32 v[50:51], v[2:3]
	v_mov_b64_e32 v[48:49], v[0:1]
	v_mov_b64_e32 v[44:45], v[12:13]
	v_mov_b64_e32 v[42:43], v[10:11]
	v_mov_b64_e32 v[40:41], v[8:9]
	v_mov_b64_e32 v[38:39], v[6:7]
	v_mov_b64_e32 v[36:37], v[4:5]
	v_mov_b64_e32 v[34:35], v[2:3]
	v_mov_b64_e32 v[32:33], v[0:1]
	v_mov_b64_e32 v[28:29], v[12:13]
	v_mov_b64_e32 v[26:27], v[10:11]
	v_mov_b64_e32 v[24:25], v[8:9]
	v_mov_b64_e32 v[22:23], v[6:7]
	v_mov_b64_e32 v[20:21], v[4:5]
	v_mov_b64_e32 v[18:19], v[2:3]
	v_mov_b64_e32 v[16:17], v[0:1]
	v_readfirstlane_b32 s40, v113
	v_readfirstlane_b32 s41, v115
	v_readfirstlane_b32 s38, v117
	v_readfirstlane_b32 s39, v119
	s_add_u32 s40, s40, s14
	s_addc_u32 s41, s41, s15
	s_add_u32 s40, s40, 0x9dc9000
	s_addc_u32 s41, s41, 0
	s_add_u32 s38, s38, s14
	s_addc_u32 s39, s39, s15
	s_add_u32 s38, s38, 0x9dc9000
	s_addc_u32 s39, s39, 0
.LBB0_161:
	s_add_i32 s8, s21, -1
	s_cmp_ge_u32 s8, s70
	s_cselect_b64 s[16:17], -1, 0
	s_and_b64 vcc, exec, s[16:17]
	s_cbranch_vccnz .LBB0_163
	s_add_i32 s8, s23, 0x8000
	s_and_b32 s8, s8, 0x18000
	s_add_i32 s8, s20, s8
	s_add_i32 s9, s8, 0x4000
	s_mov_b32 m0, s8
	s_nop 0
	global_load_lds_dwordx4 v118, s[38:39]
	s_mov_b32 m0, s9
	s_nop 0
	global_load_lds_dwordx4 v114, s[40:41]
	s_add_i32 m0, s8, 0x2000
	s_nop 0
	global_load_lds_dwordx4 v116, s[38:39]
	s_add_i32 m0, s8, 0x6000
	s_nop 0
	global_load_lds_dwordx4 v112, s[40:41]

; #define SBAR() __builtin_amdgcn_sched_barrier(0)
; template <int QH> __device__ __forceinline__ void attn_dense_body(const bf16_t* __restrict__ Qb, const bf16_t* __restrict__ Kh, const bf16_t* __restrict__ Vh,
;                                                 bf16_t* __restrict__ Ob, int seq, float scale, char* lds, const int tid) {
;     ...
;     if (j + 3 < NT) ADMA(j + 3);
;     SBAR(); qkt<QH>(pA0, pA1, KSLOT(j + 1), qr, r32, hi);
.LBB0_171:
	s_cmp_ge_u32 s21, s70
	s_cselect_b64 s[16:17], -1, 0
	s_and_b64 vcc, exec, s[16:17]
	s_cbranch_vccnz .LBB0_173
	s_add_i32 s18, s20, s25
	s_add_i32 s19, s18, 0x4000
	s_add_u32 s38, s38, 0x20000
	s_addc_u32 s39, s39, 0
	s_add_u32 s40, s40, 0x20000
	s_addc_u32 s41, s41, 0
	s_mov_b32 m0, s18
	s_nop 0
	global_load_lds_dwordx4 v118, s[38:39]
	s_mov_b32 m0, s19
	s_nop 0
	global_load_lds_dwordx4 v114, s[40:41]
	s_add_i32 m0, s18, 0x2000
	s_nop 0
	global_load_lds_dwordx4 v116, s[38:39]
	s_add_i32 m0, s18, 0x6000
	s_nop 0
	global_load_lds_dwordx4 v112, s[40:41]
	s_sub_u32 s38, s38, 0x20000
	s_subb_u32 s39, s39, 0
	s_sub_u32 s40, s40, 0x20000
	s_subb_u32 s41, s41, 0

; #define AWAIT(more) do { if (more) asm volatile("s_waitcnt vmcnt(4)" ::: "memory"); else asm volatile("s_waitcnt vmcnt(0)" ::: "memory"); } while (0)
; #define ABAR() do { asm volatile("s_waitcnt lgkmcnt(0)" ::: "memory"); __builtin_amdgcn_s_barrier(); asm volatile("" ::: "memory"); } while (0)
; #define RESC(a) do { if (__any((a) < 1.f)) { if (hi == 0) al_l[r32] = (a); asm volatile("s_waitcnt lgkmcnt(0)" ::: "memory"); \
;     for (int d = 0; d < 4; ++d) for (int r = 0; r < 16; ++r) o[d][r] *= al_l[crow(r, hi)]; } } while (0)
; __device__ __forceinline__ void partialSM(f32x16& p0, f32x16& p1, float& m_reg, float& mn, float& alpha, float C, float thr) {
;     ...
;     pmax = fmaxf(__uint_as_float(rr[0]), __uint_as_float(rr[1])); }
;   if (__builtin_expect(__all(pmax - m_reg <= thr), 1)) { mn = m_reg; alpha = 1.f; }
;   else { mn = fmaxf(m_reg, pmax); alpha = __builtin_amdgcn_exp2f((m_reg - mn) * C); m_reg = mn; }
;   float mnC = -mn * C;
;   for (int r = 0; r < 16; ++r) p0[r] = fmaf(p0[r], C, mnC); for (int r = 0; r < 16; ++r) p1[r] = fmaf(p1[r], C, mnC);
;   for (int r = 0; r < 16; ++r) p0[r] = __builtin_amdgcn_exp2f(p0[r]);
; }
; __device__ __forceinline__ void finishSM(f32x16& p0, f32x16& p1, float alpha, float& l_reg, bf16x8& pa0, bf16x8& pa1, bf16x8& pa2, bf16x8& pa3) {
;   for (int r = 0; r < 16; ++r) p1[r] = __builtin_amdgcn_exp2f(p1[r]);
;   float ps = 0; for (int r = 0; r < 16; ++r) ps += p0[r]; for (int r = 0; r < 16; ++r) ps += p1[r];
;   { auto rr = __builtin_amdgcn_permlane32_swap(__float_as_uint(ps), __float_as_uint(ps), false, false);
;     ps = __uint_as_float(rr[0]) + __uint_as_float(rr[1]); }
;   l_reg = l_reg * alpha + ps;
; template <int QH> __device__ __forceinline__ void attn_dense_body(const bf16_t* __restrict__ Qb, const bf16_t* __restrict__ Kh, const bf16_t* __restrict__ Vh,
;                                                 bf16_t* __restrict__ Ob, int seq, float scale, char* lds, const int tid) {
;     ...
;     pv_d0(o, VSLOT(j), pa0, pa1, pa2, pa3); partialSM(pA0, pA1, m_reg, mnA, alA, C, thr);
;     AWAIT(j + 3 < NT); ABAR();
;     RESC(alA);
;   }
.LBB0_181:
	v_add_f32_e32 v125, v134, v135
	v_cndmask_b32_e64 v157, v124, v121, s[8:9]
	v_fmac_f32_e32 v125, v158, v144
	v_add_f32_e32 v144, v122, v123
	v_mul_f32_e32 v122, 0xbfb8aa3b, v157
	v_mov_b32_e32 v121, v122
	v_fmamk_f32 v80, v80, 0x3fb8aa3b, v122
	v_fmamk_f32 v81, v81, 0x3fb8aa3b, v122
	v_fmamk_f32 v82, v82, 0x3fb8aa3b, v122
	v_fmamk_f32 v83, v83, 0x3fb8aa3b, v122
	v_fmamk_f32 v84, v84, 0x3fb8aa3b, v122
	v_fmamk_f32 v85, v85, 0x3fb8aa3b, v122
	v_fmamk_f32 v86, v86, 0x3fb8aa3b, v122
	v_fmamk_f32 v87, v87, 0x3fb8aa3b, v122
	v_fmamk_f32 v88, v88, 0x3fb8aa3b, v122
	v_fmamk_f32 v89, v89, 0x3fb8aa3b, v122
	v_fmamk_f32 v90, v90, 0x3fb8aa3b, v122
	v_fmamk_f32 v91, v91, 0x3fb8aa3b, v122
	v_fmamk_f32 v92, v92, 0x3fb8aa3b, v122
	v_fmamk_f32 v93, v93, 0x3fb8aa3b, v122
	v_fmamk_f32 v94, v94, 0x3fb8aa3b, v122
	v_fmac_f32_e32 v121, 0x3fb8aa3b, v95
	v_exp_f32_e32 v161, v80
	v_exp_f32_e32 v163, v81
	v_exp_f32_e32 v165, v82
	v_exp_f32_e32 v167, v83
	v_exp_f32_e32 v169, v84
	v_exp_f32_e32 v171, v85
	v_exp_f32_e32 v184, v86
	v_exp_f32_e32 v199, v87
	v_exp_f32_e32 v159, v88
	v_exp_f32_e32 v160, v89
	v_exp_f32_e32 v162, v90
	v_exp_f32_e32 v164, v91
	v_exp_f32_e32 v166, v92
	v_exp_f32_e32 v168, v93
	v_exp_f32_e32 v170, v94
	v_exp_f32_e32 v185, v121
	v_fmac_f32_e32 v144, v125, v136
	v_pk_fma_f32 v[154:155], v[64:65], s[4:5], v[122:123] op_sel_hi:[1,0,0]
	v_pk_fma_f32 v[152:153], v[66:67], s[4:5], v[122:123] op_sel_hi:[1,0,0]
	v_pk_fma_f32 v[150:151], v[68:69], s[4:5], v[122:123] op_sel_hi:[1,0,0]
	v_pk_fma_f32 v[142:143], v[70:71], s[4:5], v[122:123] op_sel_hi:[1,0,0]
	v_pk_fma_f32 v[140:141], v[72:73], s[4:5], v[122:123] op_sel_hi:[1,0,0]
	v_pk_fma_f32 v[138:139], v[74:75], s[4:5], v[122:123] op_sel_hi:[1,0,0]
	v_pk_fma_f32 v[136:137], v[76:77], s[4:5], v[122:123] op_sel_hi:[1,0,0]
	v_pk_fma_f32 v[134:135], v[78:79], s[4:5], v[122:123] op_sel_hi:[1,0,0]
	s_add_u32 s38, s38, s74
	s_addc_u32 s39, s39, s75
	s_add_u32 s40, s40, s74
	s_addc_u32 s41, s41, s75
	s_add_i32 s21, s21, 2
	s_and_b64 vcc, exec, s[16:17]
	s_cbranch_vccnz .LBB0_183
	s_mov_b32 s23, s22
	v_mov_b32_e32 v158, v120
	s_branch .LBB0_161
